# phase 1.5 (cq/ckv rmsnorm + k-rope): the four rows' loads issued together, one vmcnt(0) instead of a wait after each row
# speedup vs baseline: 1.0063x; 1.0045x over previous
; __global__ void __launch_bounds__(512, 2) mega_fwd(Args a) {
;     ...
;         for (int r = 0; r < 4; ++r) { const bf16_t* pr = Pp + (size_t)(m0 + r) * NRC; const int pos = (m0 + r) & (SEQ - 1);
;             vq[r] = (u32x4){0u, 0u, 0u, 0u}; vk[r] = (u32x4){0u, 0u, 0u, 0u}; k1[r] = 0; k2[r] = 0; cc[r] = 0.f; sn[r] = 0.f;
;             if (lane < 48) vq[r] = *(const u32x4*)(pr + R_CQ + lane * 8);
;             if (lane < 32) { vk[r] = *(const u32x4*)(pr + R_CKV + lane * 8); k1[r] = pr[R_KR + lane]; k2[r] = pr[R_KR + 32 + lane]; cc[r] = ct[pos * 32 + lane]; sn[r] = st[pos * 32 + lane]; } }
.LBB0_278:
	s_or_b64 exec, exec, s[4:5]
	v_lshl_add_u64 v[40:41], v[38:39], 0, v[34:35]
	v_mov_b32_e32 v63, 0
	v_mov_b32_e32 v24, 0
	v_mov_b32_e32 v25, 0
	v_mov_b32_e32 v26, 0
	v_mov_b32_e32 v27, 0
	v_mov_b32_e32 v64, 0
	v_mov_b32_e32 v65, 0
	s_and_saveexec_b64 s[4:5], s[8:9]
	s_cbranch_execz .LBB0_280
	s_and_b32 s23, s0, 0x3ff80
	v_add_u32_e32 v0, s23, v32
	v_ashrrev_i32_e32 v1, 31, v0
	v_lshlrev_b64 v[0:1], 2, v[0:1]
	v_lshl_add_u64 v[2:3], s[10:11], 0, v[0:1]
	global_load_dword v63, v[2:3], off
	global_load_dwordx4 v[24:27], v[38:39], off offset:768
	global_load_ushort v65, v[40:41], off offset:1280
	global_load_ushort v64, v[40:41], off offset:1344
	v_lshl_add_u64 v[0:1], s[12:13], 0, v[0:1]
	global_load_dword v62, v[0:1], off

; __global__ void __launch_bounds__(512, 2) mega_fwd(Args a) {
;     ...
;         for (int r = 0; r < 4; ++r) { const bf16_t* pr = Pp + (size_t)(m0 + r) * NRC; const int pos = (m0 + r) & (SEQ - 1);
;             vq[r] = (u32x4){0u, 0u, 0u, 0u}; vk[r] = (u32x4){0u, 0u, 0u, 0u}; k1[r] = 0; k2[r] = 0; cc[r] = 0.f; sn[r] = 0.f;
;             if (lane < 48) vq[r] = *(const u32x4*)(pr + R_CQ + lane * 8);
;             if (lane < 32) { vk[r] = *(const u32x4*)(pr + R_CKV + lane * 8); k1[r] = pr[R_KR + lane]; k2[r] = pr[R_KR + 32 + lane]; cc[r] = ct[pos * 32 + lane]; sn[r] = st[pos * 32 + lane]; } }
.LBB0_282:
	s_or_b64 exec, exec, s[4:5]
	v_mov_b32_e32 v59, 0
	v_mov_b32_e32 v16, 0
	v_mov_b32_e32 v17, 0
	v_mov_b32_e32 v18, 0
	v_mov_b32_e32 v19, 0
	v_mov_b32_e32 v60, 0
	v_mov_b32_e32 v61, 0
	s_and_saveexec_b64 s[4:5], s[8:9]
	s_cbranch_execz .LBB0_284
	v_add_co_u32_e32 v0, vcc, 0x2000, v38
	s_add_i32 s23, s0, 32
	s_nop 0
	v_addc_co_u32_e32 v1, vcc, 0, v39, vcc
	s_and_b32 s23, s23, 0x3ffa0
	global_load_dwordx4 v[16:19], v[0:1], off offset:256
	v_add_u32_e32 v0, s23, v32
	v_ashrrev_i32_e32 v1, 31, v0
	v_lshlrev_b64 v[0:1], 2, v[0:1]
	v_lshl_add_u64 v[2:3], s[10:11], 0, v[0:1]
	global_load_dword v59, v[2:3], off
	v_add_co_u32_e32 v2, vcc, 0x2000, v40
	v_lshl_add_u64 v[0:1], s[12:13], 0, v[0:1]
	s_nop 0
	v_addc_co_u32_e32 v3, vcc, 0, v41, vcc
	global_load_ushort v61, v[2:3], off offset:768
	global_load_ushort v60, v[2:3], off offset:832
	global_load_dword v58, v[0:1], off

; __global__ void __launch_bounds__(512, 2) mega_fwd(Args a) {
;     ...
;         for (int r = 0; r < 4; ++r) { const bf16_t* pr = Pp + (size_t)(m0 + r) * NRC; const int pos = (m0 + r) & (SEQ - 1);
;             vq[r] = (u32x4){0u, 0u, 0u, 0u}; vk[r] = (u32x4){0u, 0u, 0u, 0u}; k1[r] = 0; k2[r] = 0; cc[r] = 0.f; sn[r] = 0.f;
;             if (lane < 48) vq[r] = *(const u32x4*)(pr + R_CQ + lane * 8);
;             if (lane < 32) { vk[r] = *(const u32x4*)(pr + R_CKV + lane * 8); k1[r] = pr[R_KR + lane]; k2[r] = pr[R_KR + 32 + lane]; cc[r] = ct[pos * 32 + lane]; sn[r] = st[pos * 32 + lane]; } }
.LBB0_286:
	s_or_b64 exec, exec, s[4:5]
	v_mov_b32_e32 v55, 0
	v_mov_b32_e32 v8, 0
	s_waitcnt lgkmcnt(0)
	v_mov_b32_e32 v9, 0
	v_mov_b32_e32 v10, 0
	v_mov_b32_e32 v11, 0
	v_mov_b32_e32 v56, 0
	v_mov_b32_e32 v57, 0
	s_and_saveexec_b64 s[4:5], s[8:9]
	s_cbranch_execz .LBB0_288
	v_add_co_u32_e32 v0, vcc, 0x3000, v38
	s_add_i32 s23, s0, 64
	s_nop 0
	v_addc_co_u32_e32 v1, vcc, 0, v39, vcc
	s_and_b32 s23, s23, 0x3ffc0
	global_load_dwordx4 v[8:11], v[0:1], off offset:3840
	v_add_u32_e32 v0, s23, v32
	v_ashrrev_i32_e32 v1, 31, v0
	v_lshlrev_b64 v[0:1], 2, v[0:1]
	v_lshl_add_u64 v[2:3], s[10:11], 0, v[0:1]
	global_load_dword v55, v[2:3], off
	v_add_co_u32_e32 v2, vcc, 0x4000, v40
	v_lshl_add_u64 v[0:1], s[12:13], 0, v[0:1]
	s_nop 0
	v_addc_co_u32_e32 v3, vcc, 0, v41, vcc
	global_load_ushort v57, v[2:3], off offset:256
	global_load_ushort v56, v[2:3], off offset:320
	global_load_dword v54, v[0:1], off

; __device__ __forceinline__ unsigned pk2(float lo, float hi) { return f2bf(lo) | (f2bf(hi) << 16); }
; __global__ void __launch_bounds__(512, 2) mega_fwd(Args a) {
;     ...
;         for (int r = 0; r < 4; ++r) { const bf16_t* pr = Pp + (size_t)(m0 + r) * NRC; const int pos = (m0 + r) & (SEQ - 1);
;             vq[r] = (u32x4){0u, 0u, 0u, 0u}; vk[r] = (u32x4){0u, 0u, 0u, 0u}; k1[r] = 0; k2[r] = 0; cc[r] = 0.f; sn[r] = 0.f;
;             if (lane < 48) vq[r] = *(const u32x4*)(pr + R_CQ + lane * 8);
;             if (lane < 32) { vk[r] = *(const u32x4*)(pr + R_CKV + lane * 8); k1[r] = pr[R_KR + lane]; k2[r] = pr[R_KR + 32 + lane]; cc[r] = ct[pos * 32 + lane]; sn[r] = st[pos * 32 + lane]; } }
; #pragma unroll
;         for (int r = 0; r < 4; ++r) { bf16_t* pr = Pp + (size_t)(m0 + r) * NRC;
;           { const u32x4 v = vq[r]; float f[8] = {bflo(v.x), bfhi(v.x), bflo(v.y), bfhi(v.y), bflo(v.z), bfhi(v.z), bflo(v.w), bfhi(v.w)}; float sq = 0.f;
; #pragma unroll
;             for (int e = 0; e < 8; ++e) sq += f[e] * f[e];
;             const float rn = rsqrtf(wave_sum(sq) * (1.f / QLORA) + EPS);
;             if (lane < 48) { u32x4 o; o.x = pk2(f[0] * rn, f[1] * rn); o.y = pk2(f[2] * rn, f[3] * rn); o.z = pk2(f[4] * rn, f[5] * rn); o.w = pk2(f[6] * rn, f[7] * rn); *(u32x4*)(pr + R_CQ + lane * 8) = o; } }
.LBB0_292:
	s_or_b64 exec, exec, s[4:5]
	s_waitcnt vmcnt(0)
	v_lshlrev_b32_e32 v65, 16, v65
	v_lshlrev_b32_e32 v64, 16, v64
	v_lshlrev_b32_e32 v61, 16, v61
	v_lshlrev_b32_e32 v60, 16, v60
	v_lshlrev_b32_e32 v57, 16, v57
	v_lshlrev_b32_e32 v56, 16, v56
	v_lshlrev_b32_e32 v53, 16, v53
	v_lshlrev_b32_e32 v52, 16, v52
	v_lshlrev_b32_e32 v41, 16, v29
	v_lshlrev_b32_e32 v40, 16, v28
	v_and_b32_e32 v29, 0xffff0000, v29
	v_and_b32_e32 v28, 0xffff0000, v28
	v_pk_mul_f32 v[66:67], v[40:41], v[40:41]
	v_pk_mul_f32 v[68:69], v[28:29], v[28:29]
	v_lshlrev_b32_e32 v43, 16, v31
	v_add_f32_e32 v66, v66, v68
	v_lshlrev_b32_e32 v42, 16, v30
	v_add_f32_e32 v66, v66, v67
	v_and_b32_e32 v31, 0xffff0000, v31
	v_and_b32_e32 v30, 0xffff0000, v30
	v_pk_mul_f32 v[70:71], v[42:43], v[42:43]
	v_add_f32_e32 v66, v66, v69
	v_pk_mul_f32 v[72:73], v[30:31], v[30:31]
	v_add_f32_e32 v66, v66, v70
	v_add_f32_e32 v66, v66, v72
	v_add_f32_e32 v66, v66, v71
	v_add_f32_e32 v66, v66, v73
	ds_bpermute_b32 v67, v44, v66
	s_waitcnt lgkmcnt(0)
	v_add_f32_e32 v66, v66, v67
	ds_bpermute_b32 v67, v45, v66
	s_waitcnt lgkmcnt(0)
	v_add_f32_e32 v66, v66, v67
	ds_bpermute_b32 v67, v46, v66
	s_waitcnt lgkmcnt(0)
	v_add_f32_e32 v66, v66, v67
	ds_bpermute_b32 v67, v47, v66
	s_waitcnt lgkmcnt(0)
	v_add_f32_e32 v66, v66, v67
	ds_bpermute_b32 v67, v48, v66
	s_waitcnt lgkmcnt(0)
	v_add_f32_e32 v66, v66, v67
	ds_bpermute_b32 v67, v49, v66
	s_and_saveexec_b64 s[4:5], s[6:7]
	s_cbranch_execz .LBB0_294
	s_waitcnt lgkmcnt(0)
	v_add_f32_e32 v66, v66, v67
	v_fmamk_f32 v66, v66, 0x3b2aaaab, v33
	v_mul_f32_e32 v67, 0x4b800000, v66
	v_cmp_gt_f32_e32 vcc, s21, v66
	s_nop 1
	v_cndmask_b32_e32 v66, v66, v67, vcc
	v_rsq_f32_e32 v66, v66
	s_nop 0
	v_mul_f32_e32 v67, 0x45800000, v66
	v_cndmask_b32_e32 v66, v66, v67, vcc
	v_pk_mul_f32 v[28:29], v[66:67], v[28:29] op_sel_hi:[0,1]
	v_pk_mul_f32 v[30:31], v[66:67], v[30:31] op_sel_hi:[0,1]
	v_pk_mul_f32 v[40:41], v[66:67], v[40:41] op_sel_hi:[0,1]
	v_pk_mul_f32 v[42:43], v[66:67], v[42:43] op_sel_hi:[0,1]
	v_bfe_u32 v66, v31, 16, 1
	v_bfe_u32 v67, v30, 16, 1
	v_bfe_u32 v68, v29, 16, 1
	v_bfe_u32 v69, v28, 16, 1
	v_add3_u32 v28, v28, v69, s22
	v_add3_u32 v29, v29, v68, s22
	v_add3_u32 v30, v30, v67, s22
	v_add3_u32 v31, v31, v66, s22
	v_bfe_u32 v66, v40, 16, 1
	v_bfe_u32 v67, v41, 16, 1
	v_bfe_u32 v68, v42, 16, 1
	v_bfe_u32 v69, v43, 16, 1
	v_add3_u32 v43, v43, v69, s22
	v_add3_u32 v42, v42, v68, s22
	v_add3_u32 v41, v41, v67, s22
	v_add3_u32 v40, v40, v66, s22
	v_lshrrev_b32_e32 v40, 16, v40
	v_lshrrev_b32_e32 v41, 16, v41
	v_lshrrev_b32_e32 v42, 16, v42
	v_lshrrev_b32_e32 v43, 16, v43
	v_and_or_b32 v31, v31, s20, v43
	v_and_or_b32 v30, v30, s20, v42
	v_and_or_b32 v29, v29, s20, v41
	v_and_or_b32 v28, v28, s20, v40
	global_store_dwordx4 v[38:39], v[28:31], off
